# placement pin: the 16 GEMM main-loop heads aligned to 64 bytes (.p2align 6)
# speedup vs baseline: 1.0053x; 1.0016x over previous
;     __device__ __forceinline__ bool next(int i, Unit& u) const { const long L = (long)i * G + c; if (L >= map.total()) return false; map((int)L, u); return true; }
; template <class Epi, class Sched, bool SWAPD = false>
; __device__ __forceinline__ void gemm_phase(LAS unsigned char* lds, const Gemm g, const Sched& S, const Epi& E) {
;     ...
;     for (;;) {
;         const bool has_next = S.next(ui + 1, nxt);
;         const char* nA = has_next ? (const char*)g.A + nxt.aoff : cA; const char* nB = has_next ? (const char*)g.Bt + nxt.boff : cB;
;         const int nt = cur.nt ? cur.nt : ntK;
;         for (int t = 0; t < nt; t += 2) {
;             const bool last = (t == nt - 2);
;             const char* a1 = cA + (size_t)(t + 1) * kstepA;
;             const char* a2 = last ? nA : cA + (size_t)(t + 2) * kstepA; const char* b2 = last ? nB : cB + (size_t)(t + 2) * kstep;
;     ...
; #pragma unroll
;         for (int a = 0; a < 2; ++a)
; #pragma unroll
;             for (int b = 0; b < 2; ++b)
; #pragma unroll
;                 for (int m = 0; m < 4; ++m)
; #pragma unroll
;                     for (int n = 0; n < 2; ++n) acc[a][b][m][n] = (f32x4){0.f, 0.f, 0.f, 0.f};
.LBB0_255:
	s_add_u32 s28, s18, s24
	s_addc_u32 s29, s19, s25
	s_and_b64 s[38:39], s[4:5], exec
	s_cselect_b32 s13, s29, s45
	s_cselect_b32 s23, s28, s44
	s_add_u32 s38, s95, s26
	s_addc_u32 s39, s30, s27
	s_and_b64 s[50:51], s[4:5], exec
	s_cselect_b32 s64, s39, s47
	s_cselect_b32 s65, s38, s46
	s_add_u32 s44, s44, 0x40080
	s_addc_u32 s45, s45, 0
	s_add_u32 s66, s46, 0x100
	v_mov_b32_e32 v0, 0
	s_addc_u32 s67, s47, 0
	s_mov_b32 s68, -2
	v_mov_b64_e32 v[0:1], 0
	v_mov_b64_e32 v[2:3], 0
	v_mov_b64_e32 v[4:5], 0
	v_mov_b64_e32 v[6:7], 0
	v_mov_b64_e32 v[8:9], 0
	v_mov_b64_e32 v[10:11], 0
	v_mov_b64_e32 v[12:13], 0
	v_mov_b64_e32 v[14:15], 0
	v_mov_b64_e32 v[16:17], 0
	v_mov_b64_e32 v[18:19], 0
	v_mov_b64_e32 v[20:21], 0
	v_mov_b64_e32 v[22:23], 0
	v_mov_b64_e32 v[24:25], 0
	v_mov_b64_e32 v[26:27], 0
	v_mov_b64_e32 v[28:29], 0
	v_mov_b64_e32 v[30:31], 0
	v_mov_b64_e32 v[32:33], 0
	v_mov_b64_e32 v[34:35], 0
	v_mov_b64_e32 v[36:37], 0
	v_mov_b64_e32 v[38:39], 0
	v_mov_b64_e32 v[40:41], 0
	v_mov_b64_e32 v[42:43], 0
	v_mov_b64_e32 v[44:45], 0
	v_mov_b64_e32 v[46:47], 0
	v_mov_b64_e32 v[48:49], 0
	v_mov_b64_e32 v[50:51], 0
	v_mov_b64_e32 v[52:53], 0
	v_mov_b64_e32 v[54:55], 0
	v_mov_b64_e32 v[56:57], 0
	v_mov_b64_e32 v[58:59], 0
	v_mov_b64_e32 v[60:61], 0
	v_mov_b64_e32 v[62:63], 0
	v_mov_b64_e32 v[64:65], 0
	v_mov_b64_e32 v[66:67], 0
	v_mov_b64_e32 v[68:69], 0
	v_mov_b64_e32 v[70:71], 0
	v_mov_b64_e32 v[72:73], 0
	v_mov_b64_e32 v[74:75], 0
	v_mov_b64_e32 v[76:77], 0
	v_mov_b64_e32 v[78:79], 0
	v_mov_b64_e32 v[80:81], 0
	v_mov_b64_e32 v[82:83], 0
	v_mov_b64_e32 v[84:85], 0
	v_mov_b64_e32 v[86:87], 0
	v_mov_b64_e32 v[88:89], 0
	v_mov_b64_e32 v[90:91], 0
	v_mov_b64_e32 v[92:93], 0
	v_mov_b64_e32 v[94:95], 0
	v_mov_b64_e32 v[96:97], 0
	v_mov_b64_e32 v[98:99], 0
	v_mov_b64_e32 v[100:101], 0
	v_mov_b64_e32 v[102:103], 0
	v_mov_b64_e32 v[104:105], 0
	v_mov_b64_e32 v[106:107], 0
	v_mov_b64_e32 v[108:109], 0
	v_mov_b64_e32 v[110:111], 0
	v_mov_b64_e32 v[112:113], 0
	v_mov_b64_e32 v[114:115], 0
	v_mov_b64_e32 v[116:117], 0
	v_mov_b64_e32 v[118:119], 0
	v_mov_b64_e32 v[120:121], 0
	v_mov_b64_e32 v[122:123], 0
	v_mov_b64_e32 v[124:125], 0
	v_mov_b64_e32 v[126:127], 0
	.p2align 6

;     __device__ __forceinline__ bool next(int i, Unit& u) const { const long L = (long)i * G + c; if (L >= map.total()) return false; map((int)L, u); return true; }
; template <class Epi, class Sched, bool SWAPD = false>
; __device__ __forceinline__ void gemm_phase(LAS unsigned char* lds, const Gemm g, const Sched& S, const Epi& E) {
;     ...
;     for (;;) {
;         const bool has_next = S.next(ui + 1, nxt);
;         const char* nA = has_next ? (const char*)g.A + nxt.aoff : cA; const char* nB = has_next ? (const char*)g.Bt + nxt.boff : cB;
;         const int nt = cur.nt ? cur.nt : ntK;
;         for (int t = 0; t < nt; t += 2) {
;             const bool last = (t == nt - 2);
;             const char* a1 = cA + (size_t)(t + 1) * kstepA;
;             const char* a2 = last ? nA : cA + (size_t)(t + 2) * kstepA; const char* b2 = last ? nB : cB + (size_t)(t + 2) * kstep;
;     ...
; #pragma unroll
;         for (int a = 0; a < 2; ++a)
; #pragma unroll
;             for (int b = 0; b < 2; ++b)
; #pragma unroll
;                 for (int m = 0; m < 4; ++m)
; #pragma unroll
;                     for (int n = 0; n < 2; ++n) acc[a][b][m][n] = (f32x4){0.f, 0.f, 0.f, 0.f};
.LBB0_351:
	s_add_u32 s24, s14, s12
	s_addc_u32 s25, s15, s13
	s_add_u32 s26, s80, s22
	s_addc_u32 s27, s81, s23
	s_cmp_lg_u32 s29, 0
	s_cselect_b32 s0, s29, 44
	s_cmp_lt_i32 s0, 1
	s_cbranch_scc1 .LBB0_358
	s_and_b64 s[34:35], s[4:5], exec
	s_cselect_b32 s29, s25, s39
	s_cselect_b32 s33, s24, s38
	s_cselect_b32 s34, s27, s43
	s_cselect_b32 s35, s26, s42
	s_add_i32 s74, s0, -2
	s_add_u32 s75, s42, 0x100
	v_mov_b32_e32 v0, 0
	s_addc_u32 s76, s43, 0
	s_mov_b32 s44, 0
	v_mov_b64_e32 v[0:1], 0
	v_mov_b64_e32 v[2:3], 0
	v_mov_b64_e32 v[4:5], 0
	v_mov_b64_e32 v[6:7], 0
	v_mov_b64_e32 v[8:9], 0
	v_mov_b64_e32 v[10:11], 0
	v_mov_b64_e32 v[12:13], 0
	v_mov_b64_e32 v[14:15], 0
	v_mov_b64_e32 v[16:17], 0
	v_mov_b64_e32 v[18:19], 0
	v_mov_b64_e32 v[20:21], 0
	v_mov_b64_e32 v[22:23], 0
	v_mov_b64_e32 v[24:25], 0
	v_mov_b64_e32 v[26:27], 0
	v_mov_b64_e32 v[28:29], 0
	v_mov_b64_e32 v[30:31], 0
	v_mov_b64_e32 v[32:33], 0
	v_mov_b64_e32 v[34:35], 0
	v_mov_b64_e32 v[36:37], 0
	v_mov_b64_e32 v[38:39], 0
	v_mov_b64_e32 v[40:41], 0
	v_mov_b64_e32 v[42:43], 0
	v_mov_b64_e32 v[44:45], 0
	v_mov_b64_e32 v[46:47], 0
	v_mov_b64_e32 v[48:49], 0
	v_mov_b64_e32 v[50:51], 0
	v_mov_b64_e32 v[52:53], 0
	v_mov_b64_e32 v[54:55], 0
	v_mov_b64_e32 v[56:57], 0
	v_mov_b64_e32 v[58:59], 0
	v_mov_b64_e32 v[60:61], 0
	v_mov_b64_e32 v[62:63], 0
	v_mov_b64_e32 v[64:65], 0
	v_mov_b64_e32 v[66:67], 0
	v_mov_b64_e32 v[68:69], 0
	v_mov_b64_e32 v[70:71], 0
	v_mov_b64_e32 v[72:73], 0
	v_mov_b64_e32 v[74:75], 0
	v_mov_b64_e32 v[76:77], 0
	v_mov_b64_e32 v[78:79], 0
	v_mov_b64_e32 v[80:81], 0
	v_mov_b64_e32 v[82:83], 0
	v_mov_b64_e32 v[84:85], 0
	v_mov_b64_e32 v[86:87], 0
	v_mov_b64_e32 v[88:89], 0
	v_mov_b64_e32 v[90:91], 0
	v_mov_b64_e32 v[92:93], 0
	v_mov_b64_e32 v[94:95], 0
	v_mov_b64_e32 v[96:97], 0
	v_mov_b64_e32 v[98:99], 0
	v_mov_b64_e32 v[100:101], 0
	v_mov_b64_e32 v[102:103], 0
	v_mov_b64_e32 v[104:105], 0
	v_mov_b64_e32 v[106:107], 0
	v_mov_b64_e32 v[108:109], 0
	v_mov_b64_e32 v[110:111], 0
	v_mov_b64_e32 v[112:113], 0
	v_mov_b64_e32 v[114:115], 0
	v_mov_b64_e32 v[116:117], 0
	v_mov_b64_e32 v[118:119], 0
	v_mov_b64_e32 v[120:121], 0
	v_mov_b64_e32 v[122:123], 0
	v_mov_b64_e32 v[124:125], 0
	v_mov_b64_e32 v[126:127], 0
	.p2align 6

;     __device__ __forceinline__ bool next(int i, Unit& u) const { const long L = (long)i * G + c; if (L >= map.total()) return false; map((int)L, u); return true; }
; template <class Epi, class Sched, bool SWAPD = false>
; __device__ __forceinline__ void gemm_phase(LAS unsigned char* lds, const Gemm g, const Sched& S, const Epi& E) {
;     ...
;     for (;;) {
;         const bool has_next = S.next(ui + 1, nxt);
;         const char* nA = has_next ? (const char*)g.A + nxt.aoff : cA; const char* nB = has_next ? (const char*)g.Bt + nxt.boff : cB;
;         const int nt = cur.nt ? cur.nt : ntK;
;         for (int t = 0; t < nt; t += 2) {
;             const bool last = (t == nt - 2);
;             const char* a1 = cA + (size_t)(t + 1) * kstepA;
;             const char* a2 = last ? nA : cA + (size_t)(t + 2) * kstepA; const char* b2 = last ? nB : cB + (size_t)(t + 2) * kstep;
;     ...
; #pragma unroll
;         for (int a = 0; a < 2; ++a)
; #pragma unroll
;             for (int b = 0; b < 2; ++b)
; #pragma unroll
;                 for (int m = 0; m < 4; ++m)
; #pragma unroll
;                     for (int n = 0; n < 2; ++n) acc[a][b][m][n] = (f32x4){0.f, 0.f, 0.f, 0.f};
.LBB0_485:
	s_add_u32 s36, s18, s26
	s_addc_u32 s37, s19, s27
	s_and_b64 s[38:39], s[4:5], exec
	s_cselect_b32 s7, s37, s41
	s_cselect_b32 s13, s36, s40
	s_add_u32 s38, s96, s28
	s_addc_u32 s39, s97, s29
	s_and_b64 s[44:45], s[4:5], exec
	s_cselect_b32 s25, s39, s43
	s_cselect_b32 s57, s38, s42
	s_add_u32 s40, s40, 0x40080
	s_addc_u32 s41, s41, 0
	s_add_u32 s64, s42, 0x100
	v_mov_b32_e32 v0, 0
	s_addc_u32 s65, s43, 0
	s_mov_b32 s66, -2
	v_mov_b64_e32 v[0:1], 0
	v_mov_b64_e32 v[2:3], 0
	v_mov_b64_e32 v[4:5], 0
	v_mov_b64_e32 v[6:7], 0
	v_mov_b64_e32 v[8:9], 0
	v_mov_b64_e32 v[10:11], 0
	v_mov_b64_e32 v[12:13], 0
	v_mov_b64_e32 v[14:15], 0
	v_mov_b64_e32 v[16:17], 0
	v_mov_b64_e32 v[18:19], 0
	v_mov_b64_e32 v[20:21], 0
	v_mov_b64_e32 v[22:23], 0
	v_mov_b64_e32 v[24:25], 0
	v_mov_b64_e32 v[26:27], 0
	v_mov_b64_e32 v[28:29], 0
	v_mov_b64_e32 v[30:31], 0
	v_mov_b64_e32 v[32:33], 0
	v_mov_b64_e32 v[34:35], 0
	v_mov_b64_e32 v[36:37], 0
	v_mov_b64_e32 v[38:39], 0
	v_mov_b64_e32 v[40:41], 0
	v_mov_b64_e32 v[42:43], 0
	v_mov_b64_e32 v[44:45], 0
	v_mov_b64_e32 v[46:47], 0
	v_mov_b64_e32 v[48:49], 0
	v_mov_b64_e32 v[50:51], 0
	v_mov_b64_e32 v[52:53], 0
	v_mov_b64_e32 v[54:55], 0
	v_mov_b64_e32 v[56:57], 0
	v_mov_b64_e32 v[58:59], 0
	v_mov_b64_e32 v[60:61], 0
	v_mov_b64_e32 v[62:63], 0
	v_mov_b64_e32 v[64:65], 0
	v_mov_b64_e32 v[66:67], 0
	v_mov_b64_e32 v[68:69], 0
	v_mov_b64_e32 v[70:71], 0
	v_mov_b64_e32 v[72:73], 0
	v_mov_b64_e32 v[74:75], 0
	v_mov_b64_e32 v[76:77], 0
	v_mov_b64_e32 v[78:79], 0
	v_mov_b64_e32 v[80:81], 0
	v_mov_b64_e32 v[82:83], 0
	v_mov_b64_e32 v[84:85], 0
	v_mov_b64_e32 v[86:87], 0
	v_mov_b64_e32 v[88:89], 0
	v_mov_b64_e32 v[90:91], 0
	v_mov_b64_e32 v[92:93], 0
	v_mov_b64_e32 v[94:95], 0
	v_mov_b64_e32 v[96:97], 0
	v_mov_b64_e32 v[98:99], 0
	v_mov_b64_e32 v[100:101], 0
	v_mov_b64_e32 v[102:103], 0
	v_mov_b64_e32 v[104:105], 0
	v_mov_b64_e32 v[106:107], 0
	v_mov_b64_e32 v[108:109], 0
	v_mov_b64_e32 v[110:111], 0
	v_mov_b64_e32 v[112:113], 0
	v_mov_b64_e32 v[114:115], 0
	v_mov_b64_e32 v[116:117], 0
	v_mov_b64_e32 v[118:119], 0
	v_mov_b64_e32 v[120:121], 0
	v_mov_b64_e32 v[122:123], 0
	v_mov_b64_e32 v[124:125], 0
	v_mov_b64_e32 v[126:127], 0
	.p2align 6

;     __device__ __forceinline__ bool next(int i, Unit& u) const { const long L = (long)i * G + c; if (L >= map.total()) return false; map((int)L, u); return true; }
; template <class Epi, class Sched, bool SWAPD = false>
; __device__ __forceinline__ void gemm_phase(LAS unsigned char* lds, const Gemm g, const Sched& S, const Epi& E) {
;     ...
;     for (;;) {
;         const bool has_next = S.next(ui + 1, nxt);
;         const char* nA = has_next ? (const char*)g.A + nxt.aoff : cA; const char* nB = has_next ? (const char*)g.Bt + nxt.boff : cB;
;         const int nt = cur.nt ? cur.nt : ntK;
;         for (int t = 0; t < nt; t += 2) {
;             const bool last = (t == nt - 2);
;             const char* a1 = cA + (size_t)(t + 1) * kstepA;
;             const char* a2 = last ? nA : cA + (size_t)(t + 2) * kstepA; const char* b2 = last ? nB : cB + (size_t)(t + 2) * kstep;
;     ...
; #pragma unroll
;         for (int a = 0; a < 2; ++a)
; #pragma unroll
;             for (int b = 0; b < 2; ++b)
; #pragma unroll
;                 for (int m = 0; m < 4; ++m)
; #pragma unroll
;                     for (int n = 0; n < 2; ++n) acc[a][b][m][n] = (f32x4){0.f, 0.f, 0.f, 0.f};
.LBB0_632:
	s_add_u32 s44, s22, s40
	s_addc_u32 s45, s23, s41
	s_and_b64 s[46:47], s[4:5], exec
	s_cselect_b32 s75, s45, s51
	s_cselect_b32 s76, s44, s50
	s_add_u32 s46, s30, s42
	s_addc_u32 s47, s31, s43
	s_and_b64 s[54:55], s[4:5], exec
	s_cselect_b32 s77, s47, s53
	s_cselect_b32 s78, s46, s52
	s_add_u32 s79, s52, 0x100
	v_mov_b32_e32 v0, 0
	s_addc_u32 s80, s53, 0
	s_mov_b32 s81, -2
	v_mov_b64_e32 v[0:1], 0
	v_mov_b64_e32 v[2:3], 0
	v_mov_b64_e32 v[4:5], 0
	v_mov_b64_e32 v[6:7], 0
	v_mov_b64_e32 v[8:9], 0
	v_mov_b64_e32 v[10:11], 0
	v_mov_b64_e32 v[12:13], 0
	v_mov_b64_e32 v[14:15], 0
	v_mov_b64_e32 v[16:17], 0
	v_mov_b64_e32 v[18:19], 0
	v_mov_b64_e32 v[20:21], 0
	v_mov_b64_e32 v[22:23], 0
	v_mov_b64_e32 v[24:25], 0
	v_mov_b64_e32 v[26:27], 0
	v_mov_b64_e32 v[28:29], 0
	v_mov_b64_e32 v[30:31], 0
	v_mov_b64_e32 v[32:33], 0
	v_mov_b64_e32 v[34:35], 0
	v_mov_b64_e32 v[36:37], 0
	v_mov_b64_e32 v[38:39], 0
	v_mov_b64_e32 v[40:41], 0
	v_mov_b64_e32 v[42:43], 0
	v_mov_b64_e32 v[44:45], 0
	v_mov_b64_e32 v[46:47], 0
	v_mov_b64_e32 v[48:49], 0
	v_mov_b64_e32 v[50:51], 0
	v_mov_b64_e32 v[52:53], 0
	v_mov_b64_e32 v[54:55], 0
	v_mov_b64_e32 v[56:57], 0
	v_mov_b64_e32 v[58:59], 0
	v_mov_b64_e32 v[60:61], 0
	v_mov_b64_e32 v[62:63], 0
	v_mov_b64_e32 v[64:65], 0
	v_mov_b64_e32 v[66:67], 0
	v_mov_b64_e32 v[68:69], 0
	v_mov_b64_e32 v[70:71], 0
	v_mov_b64_e32 v[72:73], 0
	v_mov_b64_e32 v[74:75], 0
	v_mov_b64_e32 v[76:77], 0
	v_mov_b64_e32 v[78:79], 0
	v_mov_b64_e32 v[80:81], 0
	v_mov_b64_e32 v[82:83], 0
	v_mov_b64_e32 v[84:85], 0
	v_mov_b64_e32 v[86:87], 0
	v_mov_b64_e32 v[88:89], 0
	v_mov_b64_e32 v[90:91], 0
	v_mov_b64_e32 v[92:93], 0
	v_mov_b64_e32 v[94:95], 0
	v_mov_b64_e32 v[96:97], 0
	v_mov_b64_e32 v[98:99], 0
	v_mov_b64_e32 v[100:101], 0
	v_mov_b64_e32 v[102:103], 0
	v_mov_b64_e32 v[104:105], 0
	v_mov_b64_e32 v[106:107], 0
	v_mov_b64_e32 v[108:109], 0
	v_mov_b64_e32 v[110:111], 0
	v_mov_b64_e32 v[112:113], 0
	v_mov_b64_e32 v[114:115], 0
	v_mov_b64_e32 v[116:117], 0
	v_mov_b64_e32 v[118:119], 0
	v_mov_b64_e32 v[120:121], 0
	v_mov_b64_e32 v[122:123], 0
	v_mov_b64_e32 v[124:125], 0
	v_mov_b64_e32 v[126:127], 0
	.p2align 6

;     __device__ __forceinline__ bool next(int i, Unit& u) const { const long L = (long)i * G + c; if (L >= map.total()) return false; map((int)L, u); return true; }
; template <class Epi, class Sched, bool SWAPD = false>
; __device__ __forceinline__ void gemm_phase(LAS unsigned char* lds, const Gemm g, const Sched& S, const Epi& E) {
;     ...
;     for (;;) {
;         const bool has_next = S.next(ui + 1, nxt);
;         const char* nA = has_next ? (const char*)g.A + nxt.aoff : cA; const char* nB = has_next ? (const char*)g.Bt + nxt.boff : cB;
;         const int nt = cur.nt ? cur.nt : ntK;
;         for (int t = 0; t < nt; t += 2) {
;             const bool last = (t == nt - 2);
;             const char* a1 = cA + (size_t)(t + 1) * kstepA;
;             const char* a2 = last ? nA : cA + (size_t)(t + 2) * kstepA; const char* b2 = last ? nB : cB + (size_t)(t + 2) * kstep;
;     ...
; #pragma unroll
;         for (int a = 0; a < 2; ++a)
; #pragma unroll
;             for (int b = 0; b < 2; ++b)
; #pragma unroll
;                 for (int m = 0; m < 4; ++m)
; #pragma unroll
;                     for (int n = 0; n < 2; ++n) acc[a][b][m][n] = (f32x4){0.f, 0.f, 0.f, 0.f};
.LBB0_765:
	s_add_u32 s36, s22, s26
	s_addc_u32 s37, s23, s27
	s_and_b64 s[38:39], s[4:5], exec
	s_cselect_b32 s61, s37, s41
	s_cselect_b32 s62, s36, s40
	s_add_u32 s38, s30, s28
	s_addc_u32 s39, s31, s29
	s_and_b64 s[44:45], s[4:5], exec
	s_cselect_b32 s63, s39, s43
	s_cselect_b32 s64, s38, s42
	s_add_u32 s65, s42, 0x100
	v_mov_b32_e32 v0, 0
	s_addc_u32 s66, s43, 0
	s_mov_b32 s67, -2
	v_mov_b64_e32 v[0:1], 0
	v_mov_b64_e32 v[2:3], 0
	v_mov_b64_e32 v[4:5], 0
	v_mov_b64_e32 v[6:7], 0
	v_mov_b64_e32 v[8:9], 0
	v_mov_b64_e32 v[10:11], 0
	v_mov_b64_e32 v[12:13], 0
	v_mov_b64_e32 v[14:15], 0
	v_mov_b64_e32 v[16:17], 0
	v_mov_b64_e32 v[18:19], 0
	v_mov_b64_e32 v[20:21], 0
	v_mov_b64_e32 v[22:23], 0
	v_mov_b64_e32 v[24:25], 0
	v_mov_b64_e32 v[26:27], 0
	v_mov_b64_e32 v[28:29], 0
	v_mov_b64_e32 v[30:31], 0
	v_mov_b64_e32 v[32:33], 0
	v_mov_b64_e32 v[34:35], 0
	v_mov_b64_e32 v[36:37], 0
	v_mov_b64_e32 v[38:39], 0
	v_mov_b64_e32 v[40:41], 0
	v_mov_b64_e32 v[42:43], 0
	v_mov_b64_e32 v[44:45], 0
	v_mov_b64_e32 v[46:47], 0
	v_mov_b64_e32 v[48:49], 0
	v_mov_b64_e32 v[50:51], 0
	v_mov_b64_e32 v[52:53], 0
	v_mov_b64_e32 v[54:55], 0
	v_mov_b64_e32 v[56:57], 0
	v_mov_b64_e32 v[58:59], 0
	v_mov_b64_e32 v[60:61], 0
	v_mov_b64_e32 v[62:63], 0
	v_mov_b64_e32 v[64:65], 0
	v_mov_b64_e32 v[66:67], 0
	v_mov_b64_e32 v[68:69], 0
	v_mov_b64_e32 v[70:71], 0
	v_mov_b64_e32 v[72:73], 0
	v_mov_b64_e32 v[74:75], 0
	v_mov_b64_e32 v[76:77], 0
	v_mov_b64_e32 v[78:79], 0
	v_mov_b64_e32 v[80:81], 0
	v_mov_b64_e32 v[82:83], 0
	v_mov_b64_e32 v[84:85], 0
	v_mov_b64_e32 v[86:87], 0
	v_mov_b64_e32 v[88:89], 0
	v_mov_b64_e32 v[90:91], 0
	v_mov_b64_e32 v[92:93], 0
	v_mov_b64_e32 v[94:95], 0
	v_mov_b64_e32 v[96:97], 0
	v_mov_b64_e32 v[98:99], 0
	v_mov_b64_e32 v[100:101], 0
	v_mov_b64_e32 v[102:103], 0
	v_mov_b64_e32 v[104:105], 0
	v_mov_b64_e32 v[106:107], 0
	v_mov_b64_e32 v[108:109], 0
	v_mov_b64_e32 v[110:111], 0
	v_mov_b64_e32 v[112:113], 0
	v_mov_b64_e32 v[114:115], 0
	v_mov_b64_e32 v[116:117], 0
	v_mov_b64_e32 v[118:119], 0
	v_mov_b64_e32 v[120:121], 0
	v_mov_b64_e32 v[122:123], 0
	v_mov_b64_e32 v[124:125], 0
	v_mov_b64_e32 v[126:127], 0
	.p2align 6

;     __device__ __forceinline__ bool next(int i, Unit& u) const { const long L = (long)i * G + c; if (L >= map.total()) return false; map((int)L, u); return true; }
; template <class Epi, class Sched, bool SWAPD = false>
; __device__ __forceinline__ void gemm_phase(LAS unsigned char* lds, const Gemm g, const Sched& S, const Epi& E) {
;     ...
;     for (;;) {
;         const bool has_next = S.next(ui + 1, nxt);
;         const char* nA = has_next ? (const char*)g.A + nxt.aoff : cA; const char* nB = has_next ? (const char*)g.Bt + nxt.boff : cB;
;         const int nt = cur.nt ? cur.nt : ntK;
;         for (int t = 0; t < nt; t += 2) {
;             const bool last = (t == nt - 2);
;             const char* a1 = cA + (size_t)(t + 1) * kstepA;
;             const char* a2 = last ? nA : cA + (size_t)(t + 2) * kstepA; const char* b2 = last ? nB : cB + (size_t)(t + 2) * kstep;
;     ...
; #pragma unroll
;         for (int a = 0; a < 2; ++a)
; #pragma unroll
;             for (int b = 0; b < 2; ++b)
; #pragma unroll
;                 for (int m = 0; m < 4; ++m)
; #pragma unroll
;                     for (int n = 0; n < 2; ++n) acc[a][b][m][n] = (f32x4){0.f, 0.f, 0.f, 0.f};
.LBB0_841:
	s_add_u32 s36, s0, s26
	s_addc_u32 s37, s1, s27
	s_and_b64 s[38:39], s[4:5], exec
	v_readlane_b32 s38, v254, 8
	s_cselect_b32 s23, s37, s43
	s_cselect_b32 s25, s36, s42
	v_readlane_b32 s39, v254, 9
	s_add_u32 s38, s38, s28
	s_addc_u32 s39, s39, s29
	s_and_b64 s[46:47], s[4:5], exec
	s_cselect_b32 s35, s39, s45
	s_cselect_b32 s59, s38, s44
	s_add_u32 s60, s44, 0x100
	v_mov_b32_e32 v0, 0
	s_addc_u32 s61, s45, 0
	s_mov_b32 s62, -2
	v_mov_b64_e32 v[0:1], 0
	v_mov_b64_e32 v[2:3], 0
	v_mov_b64_e32 v[4:5], 0
	v_mov_b64_e32 v[6:7], 0
	v_mov_b64_e32 v[8:9], 0
	v_mov_b64_e32 v[10:11], 0
	v_mov_b64_e32 v[12:13], 0
	v_mov_b64_e32 v[14:15], 0
	v_mov_b64_e32 v[16:17], 0
	v_mov_b64_e32 v[18:19], 0
	v_mov_b64_e32 v[20:21], 0
	v_mov_b64_e32 v[22:23], 0
	v_mov_b64_e32 v[24:25], 0
	v_mov_b64_e32 v[26:27], 0
	v_mov_b64_e32 v[28:29], 0
	v_mov_b64_e32 v[30:31], 0
	v_mov_b64_e32 v[32:33], 0
	v_mov_b64_e32 v[34:35], 0
	v_mov_b64_e32 v[36:37], 0
	v_mov_b64_e32 v[38:39], 0
	v_mov_b64_e32 v[40:41], 0
	v_mov_b64_e32 v[42:43], 0
	v_mov_b64_e32 v[44:45], 0
	v_mov_b64_e32 v[46:47], 0
	v_mov_b64_e32 v[48:49], 0
	v_mov_b64_e32 v[50:51], 0
	v_mov_b64_e32 v[52:53], 0
	v_mov_b64_e32 v[54:55], 0
	v_mov_b64_e32 v[56:57], 0
	v_mov_b64_e32 v[58:59], 0
	v_mov_b64_e32 v[60:61], 0
	v_mov_b64_e32 v[62:63], 0
	v_mov_b64_e32 v[64:65], 0
	v_mov_b64_e32 v[66:67], 0
	v_mov_b64_e32 v[68:69], 0
	v_mov_b64_e32 v[70:71], 0
	v_mov_b64_e32 v[72:73], 0
	v_mov_b64_e32 v[74:75], 0
	v_mov_b64_e32 v[76:77], 0
	v_mov_b64_e32 v[78:79], 0
	v_mov_b64_e32 v[80:81], 0
	v_mov_b64_e32 v[82:83], 0
	v_mov_b64_e32 v[84:85], 0
	v_mov_b64_e32 v[86:87], 0
	v_mov_b64_e32 v[88:89], 0
	v_mov_b64_e32 v[90:91], 0
	v_mov_b64_e32 v[92:93], 0
	v_mov_b64_e32 v[94:95], 0
	v_mov_b64_e32 v[96:97], 0
	v_mov_b64_e32 v[98:99], 0
	v_mov_b64_e32 v[100:101], 0
	v_mov_b64_e32 v[102:103], 0
	v_mov_b64_e32 v[104:105], 0
	v_mov_b64_e32 v[106:107], 0
	v_mov_b64_e32 v[108:109], 0
	v_mov_b64_e32 v[110:111], 0
	v_mov_b64_e32 v[112:113], 0
	v_mov_b64_e32 v[114:115], 0
	v_mov_b64_e32 v[116:117], 0
	v_mov_b64_e32 v[118:119], 0
	v_mov_b64_e32 v[120:121], 0
	v_mov_b64_e32 v[122:123], 0
	v_mov_b64_e32 v[124:125], 0
	v_mov_b64_e32 v[126:127], 0
	.p2align 6

;     __device__ __forceinline__ bool next(int i, Unit& u) const { const long L = (long)i * G + c; if (L >= map.total()) return false; map((int)L, u); return true; }
; template <class Epi, class Sched, bool SWAPD = false>
; __device__ __forceinline__ void gemm_phase(LAS unsigned char* lds, const Gemm g, const Sched& S, const Epi& E) {
;     ...
;     for (;;) {
;         const bool has_next = S.next(ui + 1, nxt);
;         const char* nA = has_next ? (const char*)g.A + nxt.aoff : cA; const char* nB = has_next ? (const char*)g.Bt + nxt.boff : cB;
;         const int nt = cur.nt ? cur.nt : ntK;
;         for (int t = 0; t < nt; t += 2) {
;             const bool last = (t == nt - 2);
;             const char* a1 = cA + (size_t)(t + 1) * kstepA;
;             const char* a2 = last ? nA : cA + (size_t)(t + 2) * kstepA; const char* b2 = last ? nB : cB + (size_t)(t + 2) * kstep;
;     ...
; #pragma unroll
;         for (int a = 0; a < 2; ++a)
; #pragma unroll
;             for (int b = 0; b < 2; ++b)
; #pragma unroll
;                 for (int m = 0; m < 4; ++m)
; #pragma unroll
;                     for (int n = 0; n < 2; ++n) acc[a][b][m][n] = (f32x4){0.f, 0.f, 0.f, 0.f};
.LBB0_917:
	s_add_u32 s36, s6, s26
	s_addc_u32 s37, s7, s27
	s_and_b64 s[38:39], s[4:5], exec
	v_readlane_b32 s38, v254, 6
	s_cselect_b32 s23, s37, s43
	s_cselect_b32 s25, s36, s42
	v_readlane_b32 s39, v254, 7
	s_add_u32 s38, s38, s28
	s_addc_u32 s39, s39, s29
	s_and_b64 s[46:47], s[4:5], exec
	s_cselect_b32 s35, s39, s45
	s_cselect_b32 s41, s38, s44
	s_add_u32 s42, s42, 0x40080
	s_addc_u32 s43, s43, 0
	s_add_u32 s58, s44, 0x100
	v_mov_b32_e32 v0, 0
	s_addc_u32 s59, s45, 0
	s_mov_b32 s60, -2
	v_mov_b64_e32 v[0:1], 0
	v_mov_b64_e32 v[2:3], 0
	v_mov_b64_e32 v[4:5], 0
	v_mov_b64_e32 v[6:7], 0
	v_mov_b64_e32 v[8:9], 0
	v_mov_b64_e32 v[10:11], 0
	v_mov_b64_e32 v[12:13], 0
	v_mov_b64_e32 v[14:15], 0
	v_mov_b64_e32 v[16:17], 0
	v_mov_b64_e32 v[18:19], 0
	v_mov_b64_e32 v[20:21], 0
	v_mov_b64_e32 v[22:23], 0
	v_mov_b64_e32 v[24:25], 0
	v_mov_b64_e32 v[26:27], 0
	v_mov_b64_e32 v[28:29], 0
	v_mov_b64_e32 v[30:31], 0
	v_mov_b64_e32 v[32:33], 0
	v_mov_b64_e32 v[34:35], 0
	v_mov_b64_e32 v[36:37], 0
	v_mov_b64_e32 v[38:39], 0
	v_mov_b64_e32 v[40:41], 0
	v_mov_b64_e32 v[42:43], 0
	v_mov_b64_e32 v[44:45], 0
	v_mov_b64_e32 v[46:47], 0
	v_mov_b64_e32 v[48:49], 0
	v_mov_b64_e32 v[50:51], 0
	v_mov_b64_e32 v[52:53], 0
	v_mov_b64_e32 v[54:55], 0
	v_mov_b64_e32 v[56:57], 0
	v_mov_b64_e32 v[58:59], 0
	v_mov_b64_e32 v[60:61], 0
	v_mov_b64_e32 v[62:63], 0
	v_mov_b64_e32 v[64:65], 0
	v_mov_b64_e32 v[66:67], 0
	v_mov_b64_e32 v[68:69], 0
	v_mov_b64_e32 v[70:71], 0
	v_mov_b64_e32 v[72:73], 0
	v_mov_b64_e32 v[74:75], 0
	v_mov_b64_e32 v[76:77], 0
	v_mov_b64_e32 v[78:79], 0
	v_mov_b64_e32 v[80:81], 0
	v_mov_b64_e32 v[82:83], 0
	v_mov_b64_e32 v[84:85], 0
	v_mov_b64_e32 v[86:87], 0
	v_mov_b64_e32 v[88:89], 0
	v_mov_b64_e32 v[90:91], 0
	v_mov_b64_e32 v[92:93], 0
	v_mov_b64_e32 v[94:95], 0
	v_mov_b64_e32 v[96:97], 0
	v_mov_b64_e32 v[98:99], 0
	v_mov_b64_e32 v[100:101], 0
	v_mov_b64_e32 v[102:103], 0
	v_mov_b64_e32 v[104:105], 0
	v_mov_b64_e32 v[106:107], 0
	v_mov_b64_e32 v[108:109], 0
	v_mov_b64_e32 v[110:111], 0
	v_mov_b64_e32 v[112:113], 0
	v_mov_b64_e32 v[114:115], 0
	v_mov_b64_e32 v[116:117], 0
	v_mov_b64_e32 v[118:119], 0
	v_mov_b64_e32 v[120:121], 0
	v_mov_b64_e32 v[122:123], 0
	v_mov_b64_e32 v[124:125], 0
	v_mov_b64_e32 v[126:127], 0
	.p2align 6

;     __device__ __forceinline__ bool next(int i, Unit& u) const { const long L = (long)i * G + c; if (L >= map.total()) return false; map((int)L, u); return true; }
; template <class Epi, class Sched, bool SWAPD = false>
; __device__ __forceinline__ void gemm_phase(LAS unsigned char* lds, const Gemm g, const Sched& S, const Epi& E) {
;     ...
;     for (;;) {
;         const bool has_next = S.next(ui + 1, nxt);
;         const char* nA = has_next ? (const char*)g.A + nxt.aoff : cA; const char* nB = has_next ? (const char*)g.Bt + nxt.boff : cB;
;         const int nt = cur.nt ? cur.nt : ntK;
;         for (int t = 0; t < nt; t += 2) {
;             const bool last = (t == nt - 2);
;             const char* a1 = cA + (size_t)(t + 1) * kstepA;
;             const char* a2 = last ? nA : cA + (size_t)(t + 2) * kstepA; const char* b2 = last ? nB : cB + (size_t)(t + 2) * kstep;
;     ...
; #pragma unroll
;         for (int a = 0; a < 2; ++a)
; #pragma unroll
;             for (int b = 0; b < 2; ++b)
; #pragma unroll
;                 for (int m = 0; m < 4; ++m)
; #pragma unroll
;                     for (int n = 0; n < 2; ++n) acc[a][b][m][n] = (f32x4){0.f, 0.f, 0.f, 0.f};
.LBB0_1043:
	s_add_u32 s36, s18, s28
	s_addc_u32 s37, s19, s29
	s_and_b64 s[38:39], s[4:5], exec
	s_cselect_b32 s25, s37, s43
	s_cselect_b32 s27, s36, s42
	s_add_u32 s38, s21, s34
	s_addc_u32 s39, s23, s35
	s_and_b64 s[46:47], s[4:5], exec
	s_cselect_b32 s59, s39, s45
	s_cselect_b32 s60, s38, s44
	s_add_u32 s42, s42, 0x40080
	s_addc_u32 s43, s43, 0
	s_add_u32 s61, s44, 0x100
	v_mov_b32_e32 v0, 0
	s_addc_u32 s62, s45, 0
	s_mov_b32 s63, -2
	v_mov_b64_e32 v[0:1], 0
	v_mov_b64_e32 v[2:3], 0
	v_mov_b64_e32 v[4:5], 0
	v_mov_b64_e32 v[6:7], 0
	v_mov_b64_e32 v[8:9], 0
	v_mov_b64_e32 v[10:11], 0
	v_mov_b64_e32 v[12:13], 0
	v_mov_b64_e32 v[14:15], 0
	v_mov_b64_e32 v[16:17], 0
	v_mov_b64_e32 v[18:19], 0
	v_mov_b64_e32 v[20:21], 0
	v_mov_b64_e32 v[22:23], 0
	v_mov_b64_e32 v[24:25], 0
	v_mov_b64_e32 v[26:27], 0
	v_mov_b64_e32 v[28:29], 0
	v_mov_b64_e32 v[30:31], 0
	v_mov_b64_e32 v[32:33], 0
	v_mov_b64_e32 v[34:35], 0
	v_mov_b64_e32 v[36:37], 0
	v_mov_b64_e32 v[38:39], 0
	v_mov_b64_e32 v[40:41], 0
	v_mov_b64_e32 v[42:43], 0
	v_mov_b64_e32 v[44:45], 0
	v_mov_b64_e32 v[46:47], 0
	v_mov_b64_e32 v[48:49], 0
	v_mov_b64_e32 v[50:51], 0
	v_mov_b64_e32 v[52:53], 0
	v_mov_b64_e32 v[54:55], 0
	v_mov_b64_e32 v[56:57], 0
	v_mov_b64_e32 v[58:59], 0
	v_mov_b64_e32 v[60:61], 0
	v_mov_b64_e32 v[62:63], 0
	v_mov_b64_e32 v[64:65], 0
	v_mov_b64_e32 v[66:67], 0
	v_mov_b64_e32 v[68:69], 0
	v_mov_b64_e32 v[70:71], 0
	v_mov_b64_e32 v[72:73], 0
	v_mov_b64_e32 v[74:75], 0
	v_mov_b64_e32 v[76:77], 0
	v_mov_b64_e32 v[78:79], 0
	v_mov_b64_e32 v[80:81], 0
	v_mov_b64_e32 v[82:83], 0
	v_mov_b64_e32 v[84:85], 0
	v_mov_b64_e32 v[86:87], 0
	v_mov_b64_e32 v[88:89], 0
	v_mov_b64_e32 v[90:91], 0
	v_mov_b64_e32 v[92:93], 0
	v_mov_b64_e32 v[94:95], 0
	v_mov_b64_e32 v[96:97], 0
	v_mov_b64_e32 v[98:99], 0
	v_mov_b64_e32 v[100:101], 0
	v_mov_b64_e32 v[102:103], 0
	v_mov_b64_e32 v[104:105], 0
	v_mov_b64_e32 v[106:107], 0
	v_mov_b64_e32 v[108:109], 0
	v_mov_b64_e32 v[110:111], 0
	v_mov_b64_e32 v[112:113], 0
	v_mov_b64_e32 v[114:115], 0
	v_mov_b64_e32 v[116:117], 0
	v_mov_b64_e32 v[118:119], 0
	v_mov_b64_e32 v[120:121], 0
	v_mov_b64_e32 v[122:123], 0
	v_mov_b64_e32 v[124:125], 0
	v_mov_b64_e32 v[126:127], 0
	.p2align 6

;     __device__ __forceinline__ bool next(int i, Unit& u) const { const long L = (long)i * G + c; if (L >= map.total()) return false; map((int)L, u); return true; }
; template <class Epi, class Sched, bool SWAPD = false>
; __device__ __forceinline__ void gemm_phase(LAS unsigned char* lds, const Gemm g, const Sched& S, const Epi& E) {
;     ...
;     for (;;) {
;         const bool has_next = S.next(ui + 1, nxt);
;         const char* nA = has_next ? (const char*)g.A + nxt.aoff : cA; const char* nB = has_next ? (const char*)g.Bt + nxt.boff : cB;
;         const int nt = cur.nt ? cur.nt : ntK;
;         for (int t = 0; t < nt; t += 2) {
;             const bool last = (t == nt - 2);
;             const char* a1 = cA + (size_t)(t + 1) * kstepA;
;             const char* a2 = last ? nA : cA + (size_t)(t + 2) * kstepA; const char* b2 = last ? nB : cB + (size_t)(t + 2) * kstep;
;     ...
; #pragma unroll
;         for (int a = 0; a < 2; ++a)
; #pragma unroll
;             for (int b = 0; b < 2; ++b)
; #pragma unroll
;                 for (int m = 0; m < 4; ++m)
; #pragma unroll
;                     for (int n = 0; n < 2; ++n) acc[a][b][m][n] = (f32x4){0.f, 0.f, 0.f, 0.f};
.LBB0_1120:
	s_add_u32 s26, s14, s22
	s_addc_u32 s27, s15, s23
	s_and_b64 s[28:29], s[6:7], exec
	s_cselect_b32 s58, s27, s35
	s_cselect_b32 s59, s26, s34
	s_add_u32 s28, s21, s24
	s_addc_u32 s29, s30, s25
	s_and_b64 s[38:39], s[6:7], exec
	s_cselect_b32 s60, s29, s37
	s_cselect_b32 s61, s28, s36
	s_add_u32 s62, s36, 0x100
	v_mov_b32_e32 v0, 0
	s_addc_u32 s63, s37, 0
	s_mov_b32 s64, -2
	v_mov_b64_e32 v[0:1], 0
	v_mov_b64_e32 v[2:3], 0
	v_mov_b64_e32 v[4:5], 0
	v_mov_b64_e32 v[6:7], 0
	v_mov_b64_e32 v[8:9], 0
	v_mov_b64_e32 v[10:11], 0
	v_mov_b64_e32 v[12:13], 0
	v_mov_b64_e32 v[14:15], 0
	v_mov_b64_e32 v[16:17], 0
	v_mov_b64_e32 v[18:19], 0
	v_mov_b64_e32 v[20:21], 0
	v_mov_b64_e32 v[22:23], 0
	v_mov_b64_e32 v[24:25], 0
	v_mov_b64_e32 v[26:27], 0
	v_mov_b64_e32 v[28:29], 0
	v_mov_b64_e32 v[30:31], 0
	v_mov_b64_e32 v[32:33], 0
	v_mov_b64_e32 v[34:35], 0
	v_mov_b64_e32 v[36:37], 0
	v_mov_b64_e32 v[38:39], 0
	v_mov_b64_e32 v[40:41], 0
	v_mov_b64_e32 v[42:43], 0
	v_mov_b64_e32 v[44:45], 0
	v_mov_b64_e32 v[46:47], 0
	v_mov_b64_e32 v[48:49], 0
	v_mov_b64_e32 v[50:51], 0
	v_mov_b64_e32 v[52:53], 0
	v_mov_b64_e32 v[54:55], 0
	v_mov_b64_e32 v[56:57], 0
	v_mov_b64_e32 v[58:59], 0
	v_mov_b64_e32 v[60:61], 0
	v_mov_b64_e32 v[62:63], 0
	v_mov_b64_e32 v[64:65], 0
	v_mov_b64_e32 v[66:67], 0
	v_mov_b64_e32 v[68:69], 0
	v_mov_b64_e32 v[70:71], 0
	v_mov_b64_e32 v[72:73], 0
	v_mov_b64_e32 v[74:75], 0
	v_mov_b64_e32 v[76:77], 0
	v_mov_b64_e32 v[78:79], 0
	v_mov_b64_e32 v[80:81], 0
	v_mov_b64_e32 v[82:83], 0
	v_mov_b64_e32 v[84:85], 0
	v_mov_b64_e32 v[86:87], 0
	v_mov_b64_e32 v[88:89], 0
	v_mov_b64_e32 v[90:91], 0
	v_mov_b64_e32 v[92:93], 0
	v_mov_b64_e32 v[94:95], 0
	v_mov_b64_e32 v[96:97], 0
	v_mov_b64_e32 v[98:99], 0
	v_mov_b64_e32 v[100:101], 0
	v_mov_b64_e32 v[102:103], 0
	v_mov_b64_e32 v[104:105], 0
	v_mov_b64_e32 v[106:107], 0
	v_mov_b64_e32 v[108:109], 0
	v_mov_b64_e32 v[110:111], 0
	v_mov_b64_e32 v[112:113], 0
	v_mov_b64_e32 v[114:115], 0
	v_mov_b64_e32 v[116:117], 0
	v_mov_b64_e32 v[118:119], 0
	v_mov_b64_e32 v[120:121], 0
	v_mov_b64_e32 v[122:123], 0
	v_mov_b64_e32 v[124:125], 0
	v_mov_b64_e32 v[126:127], 0
	.p2align 6

;     __device__ __forceinline__ bool next(int i, Unit& u) const { const long L = (long)i * G + c; if (L >= map.total()) return false; map((int)L, u); return true; }
; template <class Epi, class Sched, bool SWAPD = false>
; __device__ __forceinline__ void gemm_phase(LAS unsigned char* lds, const Gemm g, const Sched& S, const Epi& E) {
;     ...
;     for (;;) {
;         const bool has_next = S.next(ui + 1, nxt);
;         const char* nA = has_next ? (const char*)g.A + nxt.aoff : cA; const char* nB = has_next ? (const char*)g.Bt + nxt.boff : cB;
;         const int nt = cur.nt ? cur.nt : ntK;
;         for (int t = 0; t < nt; t += 2) {
;             const bool last = (t == nt - 2);
;             const char* a1 = cA + (size_t)(t + 1) * kstepA;
;             const char* a2 = last ? nA : cA + (size_t)(t + 2) * kstepA; const char* b2 = last ? nB : cB + (size_t)(t + 2) * kstep;
;     ...
; #pragma unroll
;         for (int a = 0; a < 2; ++a)
; #pragma unroll
;             for (int b = 0; b < 2; ++b)
; #pragma unroll
;                 for (int m = 0; m < 4; ++m)
; #pragma unroll
;                     for (int n = 0; n < 2; ++n) acc[a][b][m][n] = (f32x4){0.f, 0.f, 0.f, 0.f};
.LBB0_1246:
	s_add_u32 s36, s18, s28
	s_addc_u32 s37, s19, s29
	s_and_b64 s[38:39], s[6:7], exec
	s_cselect_b32 s25, s37, s43
	s_cselect_b32 s27, s36, s42
	s_add_u32 s38, s21, s34
	s_addc_u32 s39, s23, s35
	s_and_b64 s[46:47], s[6:7], exec
	s_cselect_b32 s59, s39, s45
	s_cselect_b32 s60, s38, s44
	s_add_u32 s42, s42, 0x40080
	s_addc_u32 s43, s43, 0
	s_add_u32 s61, s44, 0x100
	v_mov_b32_e32 v0, 0
	s_addc_u32 s62, s45, 0
	s_mov_b32 s63, -2
	v_mov_b64_e32 v[0:1], 0
	v_mov_b64_e32 v[2:3], 0
	v_mov_b64_e32 v[4:5], 0
	v_mov_b64_e32 v[6:7], 0
	v_mov_b64_e32 v[8:9], 0
	v_mov_b64_e32 v[10:11], 0
	v_mov_b64_e32 v[12:13], 0
	v_mov_b64_e32 v[14:15], 0
	v_mov_b64_e32 v[16:17], 0
	v_mov_b64_e32 v[18:19], 0
	v_mov_b64_e32 v[20:21], 0
	v_mov_b64_e32 v[22:23], 0
	v_mov_b64_e32 v[24:25], 0
	v_mov_b64_e32 v[26:27], 0
	v_mov_b64_e32 v[28:29], 0
	v_mov_b64_e32 v[30:31], 0
	v_mov_b64_e32 v[32:33], 0
	v_mov_b64_e32 v[34:35], 0
	v_mov_b64_e32 v[36:37], 0
	v_mov_b64_e32 v[38:39], 0
	v_mov_b64_e32 v[40:41], 0
	v_mov_b64_e32 v[42:43], 0
	v_mov_b64_e32 v[44:45], 0
	v_mov_b64_e32 v[46:47], 0
	v_mov_b64_e32 v[48:49], 0
	v_mov_b64_e32 v[50:51], 0
	v_mov_b64_e32 v[52:53], 0
	v_mov_b64_e32 v[54:55], 0
	v_mov_b64_e32 v[56:57], 0
	v_mov_b64_e32 v[58:59], 0
	v_mov_b64_e32 v[60:61], 0
	v_mov_b64_e32 v[62:63], 0
	v_mov_b64_e32 v[64:65], 0
	v_mov_b64_e32 v[66:67], 0
	v_mov_b64_e32 v[68:69], 0
	v_mov_b64_e32 v[70:71], 0
	v_mov_b64_e32 v[72:73], 0
	v_mov_b64_e32 v[74:75], 0
	v_mov_b64_e32 v[76:77], 0
	v_mov_b64_e32 v[78:79], 0
	v_mov_b64_e32 v[80:81], 0
	v_mov_b64_e32 v[82:83], 0
	v_mov_b64_e32 v[84:85], 0
	v_mov_b64_e32 v[86:87], 0
	v_mov_b64_e32 v[88:89], 0
	v_mov_b64_e32 v[90:91], 0
	v_mov_b64_e32 v[92:93], 0
	v_mov_b64_e32 v[94:95], 0
	v_mov_b64_e32 v[96:97], 0
	v_mov_b64_e32 v[98:99], 0
	v_mov_b64_e32 v[100:101], 0
	v_mov_b64_e32 v[102:103], 0
	v_mov_b64_e32 v[104:105], 0
	v_mov_b64_e32 v[106:107], 0
	v_mov_b64_e32 v[108:109], 0
	v_mov_b64_e32 v[110:111], 0
	v_mov_b64_e32 v[112:113], 0
	v_mov_b64_e32 v[114:115], 0
	v_mov_b64_e32 v[116:117], 0
	v_mov_b64_e32 v[118:119], 0
	v_mov_b64_e32 v[120:121], 0
	v_mov_b64_e32 v[122:123], 0
	v_mov_b64_e32 v[124:125], 0
	v_mov_b64_e32 v[126:127], 0
	.p2align 6

;     __device__ __forceinline__ bool next(int i, Unit& u) const { const long L = (long)i * G + c; if (L >= map.total()) return false; map((int)L, u); return true; }
; template <class Epi, class Sched, bool SWAPD = false>
; __device__ __forceinline__ void gemm_phase(LAS unsigned char* lds, const Gemm g, const Sched& S, const Epi& E) {
;     ...
;     for (;;) {
;         const bool has_next = S.next(ui + 1, nxt);
;         const char* nA = has_next ? (const char*)g.A + nxt.aoff : cA; const char* nB = has_next ? (const char*)g.Bt + nxt.boff : cB;
;         const int nt = cur.nt ? cur.nt : ntK;
;         for (int t = 0; t < nt; t += 2) {
;             const bool last = (t == nt - 2);
;             const char* a1 = cA + (size_t)(t + 1) * kstepA;
;             const char* a2 = last ? nA : cA + (size_t)(t + 2) * kstepA; const char* b2 = last ? nB : cB + (size_t)(t + 2) * kstep;
;     ...
; #pragma unroll
;         for (int a = 0; a < 2; ++a)
; #pragma unroll
;             for (int b = 0; b < 2; ++b)
; #pragma unroll
;                 for (int m = 0; m < 4; ++m)
; #pragma unroll
;                     for (int n = 0; n < 2; ++n) acc[a][b][m][n] = (f32x4){0.f, 0.f, 0.f, 0.f};
.LBB0_1530:
	s_add_u32 s36, s14, s28
	s_addc_u32 s37, s15, s29
	s_and_b64 s[38:39], s[6:7], exec
	s_cselect_b32 s9, s37, s41
	s_cselect_b32 s25, s36, s40
	s_add_u32 s38, s30, s34
	s_addc_u32 s39, s31, s35
	s_and_b64 s[44:45], s[6:7], exec
	s_cselect_b32 s27, s39, s43
	s_cselect_b32 s58, s38, s42
	s_add_u32 s40, s40, 0x20080
	s_addc_u32 s41, s41, 0
	s_add_u32 s59, s42, 0x100
	v_mov_b32_e32 v0, 0
	s_addc_u32 s60, s43, 0
	s_mov_b32 s61, -2
	v_mov_b64_e32 v[0:1], 0
	v_mov_b64_e32 v[2:3], 0
	v_mov_b64_e32 v[4:5], 0
	v_mov_b64_e32 v[6:7], 0
	v_mov_b64_e32 v[8:9], 0
	v_mov_b64_e32 v[10:11], 0
	v_mov_b64_e32 v[12:13], 0
	v_mov_b64_e32 v[14:15], 0
	v_mov_b64_e32 v[16:17], 0
	v_mov_b64_e32 v[18:19], 0
	v_mov_b64_e32 v[20:21], 0
	v_mov_b64_e32 v[22:23], 0
	v_mov_b64_e32 v[24:25], 0
	v_mov_b64_e32 v[26:27], 0
	v_mov_b64_e32 v[28:29], 0
	v_mov_b64_e32 v[30:31], 0
	v_mov_b64_e32 v[32:33], 0
	v_mov_b64_e32 v[34:35], 0
	v_mov_b64_e32 v[36:37], 0
	v_mov_b64_e32 v[38:39], 0
	v_mov_b64_e32 v[40:41], 0
	v_mov_b64_e32 v[42:43], 0
	v_mov_b64_e32 v[44:45], 0
	v_mov_b64_e32 v[46:47], 0
	v_mov_b64_e32 v[48:49], 0
	v_mov_b64_e32 v[50:51], 0
	v_mov_b64_e32 v[52:53], 0
	v_mov_b64_e32 v[54:55], 0
	v_mov_b64_e32 v[56:57], 0
	v_mov_b64_e32 v[58:59], 0
	v_mov_b64_e32 v[60:61], 0
	v_mov_b64_e32 v[62:63], 0
	v_mov_b64_e32 v[64:65], 0
	v_mov_b64_e32 v[66:67], 0
	v_mov_b64_e32 v[68:69], 0
	v_mov_b64_e32 v[70:71], 0
	v_mov_b64_e32 v[72:73], 0
	v_mov_b64_e32 v[74:75], 0
	v_mov_b64_e32 v[76:77], 0
	v_mov_b64_e32 v[78:79], 0
	v_mov_b64_e32 v[80:81], 0
	v_mov_b64_e32 v[82:83], 0
	v_mov_b64_e32 v[84:85], 0
	v_mov_b64_e32 v[86:87], 0
	v_mov_b64_e32 v[88:89], 0
	v_mov_b64_e32 v[90:91], 0
	v_mov_b64_e32 v[92:93], 0
	v_mov_b64_e32 v[94:95], 0
	v_mov_b64_e32 v[96:97], 0
	v_mov_b64_e32 v[98:99], 0
	v_mov_b64_e32 v[100:101], 0
	v_mov_b64_e32 v[102:103], 0
	v_mov_b64_e32 v[104:105], 0
	v_mov_b64_e32 v[106:107], 0
	v_mov_b64_e32 v[108:109], 0
	v_mov_b64_e32 v[110:111], 0
	v_mov_b64_e32 v[112:113], 0
	v_mov_b64_e32 v[114:115], 0
	v_mov_b64_e32 v[116:117], 0
	v_mov_b64_e32 v[118:119], 0
	v_mov_b64_e32 v[120:121], 0
	v_mov_b64_e32 v[122:123], 0
	v_mov_b64_e32 v[124:125], 0
	v_mov_b64_e32 v[126:127], 0
	.p2align 6

; template <class Epi, class Sched, bool SWAPD = false>
; __device__ __forceinline__ void gemm_phase(LAS unsigned char* lds, const Gemm g, const Sched& S, const Epi& E) {
;     ...
; #pragma unroll
;         for (int a = 0; a < 2; ++a)
; #pragma unroll
;             for (int b = 0; b < 2; ++b)
; #pragma unroll
;                 for (int m = 0; m < 4; ++m)
; #pragma unroll
;                     for (int n = 0; n < 2; ++n) acc[a][b][m][n] = (f32x4){0.f, 0.f, 0.f, 0.f};
;         cur = nxt; cA = nA; cB = nB; ++ui;
;     __device__ __forceinline__ bool next(int i, Unit& u) const { const long L = (long)i * G + c; if (L >= map.total()) return false; map((int)L, u); return true; }
.LBB0_1660:
	s_add_i32 s55, s55, 1
	s_mul_i32 s6, s55, s3
	s_mul_hi_u32 s7, s55, s90
	s_add_i32 s7, s7, s6
	s_mul_i32 s6, s55, s90
	s_mov_b64 s[44:45], s[12:13]
	s_mov_b64 s[12:13], s[42:43]
	s_add_u32 s42, s6, s2
	s_mov_b32 s69, s8
	s_addc_u32 s43, s7, s70
	s_ashr_i32 s8, s42, 2
	s_mov_b32 s68, s29
	s_and_b32 s29, s42, 3
	s_ashr_i32 s9, s8, 31
	v_cmp_lt_i64_e64 s[6:7], s[42:43], v[142:143]
	s_lshl_b32 s46, s29, 10
	s_lshl_b64 s[42:43], s[8:9], 20
	s_or_b32 s42, s42, s46
	s_and_b64 s[46:47], s[6:7], exec
	s_cselect_b32 s12, s42, s12
	s_cselect_b32 s9, s43, s13
	s_add_u32 s12, s18, s12
	s_addc_u32 s13, s19, s9
	s_and_b64 s[46:47], s[6:7], exec
	s_cselect_b32 s9, s13, s45
	s_cselect_b32 s74, s12, s44
	s_add_u32 s75, s44, 0x100
	v_mov_b32_e32 v0, 0
	s_addc_u32 s76, s45, 0
	v_lshl_add_u64 v[144:145], s[44:45], 0, v[138:139]
	v_lshl_add_u64 v[146:147], s[44:45], 0, v[140:141]
	s_mov_b32 s77, -2
	s_mov_b64 s[44:45], 0
	v_mov_b64_e32 v[0:1], 0
	v_mov_b64_e32 v[2:3], 0
	v_mov_b64_e32 v[4:5], 0
	v_mov_b64_e32 v[6:7], 0
	v_mov_b64_e32 v[8:9], 0
	v_mov_b64_e32 v[10:11], 0
	v_mov_b64_e32 v[12:13], 0
	v_mov_b64_e32 v[14:15], 0
	v_mov_b64_e32 v[16:17], 0
	v_mov_b64_e32 v[18:19], 0
	v_mov_b64_e32 v[20:21], 0
	v_mov_b64_e32 v[22:23], 0
	v_mov_b64_e32 v[24:25], 0
	v_mov_b64_e32 v[26:27], 0
	v_mov_b64_e32 v[28:29], 0
	v_mov_b64_e32 v[30:31], 0
	v_mov_b64_e32 v[32:33], 0
	v_mov_b64_e32 v[34:35], 0
	v_mov_b64_e32 v[36:37], 0
	v_mov_b64_e32 v[38:39], 0
	v_mov_b64_e32 v[40:41], 0
	v_mov_b64_e32 v[42:43], 0
	v_mov_b64_e32 v[44:45], 0
	v_mov_b64_e32 v[46:47], 0
	v_mov_b64_e32 v[48:49], 0
	v_mov_b64_e32 v[50:51], 0
	v_mov_b64_e32 v[52:53], 0
	v_mov_b64_e32 v[54:55], 0
	v_mov_b64_e32 v[56:57], 0
	v_mov_b64_e32 v[58:59], 0
	v_mov_b64_e32 v[60:61], 0
	v_mov_b64_e32 v[62:63], 0
	v_mov_b64_e32 v[64:65], 0
	v_mov_b64_e32 v[66:67], 0
	v_mov_b64_e32 v[68:69], 0
	v_mov_b64_e32 v[70:71], 0
	v_mov_b64_e32 v[72:73], 0
	v_mov_b64_e32 v[74:75], 0
	v_mov_b64_e32 v[76:77], 0
	v_mov_b64_e32 v[78:79], 0
	v_mov_b64_e32 v[80:81], 0
	v_mov_b64_e32 v[82:83], 0
	v_mov_b64_e32 v[84:85], 0
	v_mov_b64_e32 v[86:87], 0
	v_mov_b64_e32 v[88:89], 0
	v_mov_b64_e32 v[90:91], 0
	v_mov_b64_e32 v[92:93], 0
	v_mov_b64_e32 v[94:95], 0
	v_mov_b64_e32 v[96:97], 0
	v_mov_b64_e32 v[98:99], 0
	v_mov_b64_e32 v[100:101], 0
	v_mov_b64_e32 v[102:103], 0
	v_mov_b64_e32 v[104:105], 0
	v_mov_b64_e32 v[106:107], 0
	v_mov_b64_e32 v[108:109], 0
	v_mov_b64_e32 v[110:111], 0
	v_mov_b64_e32 v[112:113], 0
	v_mov_b64_e32 v[114:115], 0
	v_mov_b64_e32 v[116:117], 0
	v_mov_b64_e32 v[118:119], 0
	v_mov_b64_e32 v[120:121], 0
	v_mov_b64_e32 v[122:123], 0
	v_mov_b64_e32 v[124:125], 0
	v_mov_b64_e32 v[126:127], 0
	.p2align 6

;     __device__ __forceinline__ bool next(int i, Unit& u) const { const long L = (long)i * G + c; if (L >= map.total()) return false; map((int)L, u); return true; }
; template <class Epi, class Sched, bool SWAPD = false>
; __device__ __forceinline__ void gemm_phase(LAS unsigned char* lds, const Gemm g, const Sched& S, const Epi& E) {
;     ...
;     for (;;) {
;         const bool has_next = S.next(ui + 1, nxt);
;         const char* nA = has_next ? (const char*)g.A + nxt.aoff : cA; const char* nB = has_next ? (const char*)g.Bt + nxt.boff : cB;
;         const int nt = cur.nt ? cur.nt : ntK;
;         for (int t = 0; t < nt; t += 2) {
;             const bool last = (t == nt - 2);
;             const char* a1 = cA + (size_t)(t + 1) * kstepA;
;             const char* a2 = last ? nA : cA + (size_t)(t + 2) * kstepA; const char* b2 = last ? nB : cB + (size_t)(t + 2) * kstep;
;     ...
; #pragma unroll
;         for (int a = 0; a < 2; ++a)
; #pragma unroll
;             for (int b = 0; b < 2; ++b)
; #pragma unroll
;                 for (int m = 0; m < 4; ++m)
; #pragma unroll
;                     for (int n = 0; n < 2; ++n) acc[a][b][m][n] = (f32x4){0.f, 0.f, 0.f, 0.f};
.LBB0_1736:
	s_add_u32 s34, s14, s26
	s_addc_u32 s35, s15, s27
	s_and_b64 s[36:37], s[6:7], exec
	s_cselect_b32 s23, s35, s41
	s_cselect_b32 s25, s34, s40
	s_add_u32 s36, s96, s28
	s_addc_u32 s37, s97, s29
	s_and_b64 s[44:45], s[6:7], exec
	s_cselect_b32 s56, s37, s43
	s_cselect_b32 s57, s36, s42
	s_add_u32 s40, s40, 0x40080
	s_addc_u32 s41, s41, 0
	s_add_u32 s58, s42, 0x100
	v_mov_b32_e32 v0, 0
	s_addc_u32 s59, s43, 0
	s_mov_b32 s60, -2
	v_mov_b64_e32 v[0:1], 0
	v_mov_b64_e32 v[2:3], 0
	v_mov_b64_e32 v[4:5], 0
	v_mov_b64_e32 v[6:7], 0
	v_mov_b64_e32 v[8:9], 0
	v_mov_b64_e32 v[10:11], 0
	v_mov_b64_e32 v[12:13], 0
	v_mov_b64_e32 v[14:15], 0
	v_mov_b64_e32 v[16:17], 0
	v_mov_b64_e32 v[18:19], 0
	v_mov_b64_e32 v[20:21], 0
	v_mov_b64_e32 v[22:23], 0
	v_mov_b64_e32 v[24:25], 0
	v_mov_b64_e32 v[26:27], 0
	v_mov_b64_e32 v[28:29], 0
	v_mov_b64_e32 v[30:31], 0
	v_mov_b64_e32 v[32:33], 0
	v_mov_b64_e32 v[34:35], 0
	v_mov_b64_e32 v[36:37], 0
	v_mov_b64_e32 v[38:39], 0
	v_mov_b64_e32 v[40:41], 0
	v_mov_b64_e32 v[42:43], 0
	v_mov_b64_e32 v[44:45], 0
	v_mov_b64_e32 v[46:47], 0
	v_mov_b64_e32 v[48:49], 0
	v_mov_b64_e32 v[50:51], 0
	v_mov_b64_e32 v[52:53], 0
	v_mov_b64_e32 v[54:55], 0
	v_mov_b64_e32 v[56:57], 0
	v_mov_b64_e32 v[58:59], 0
	v_mov_b64_e32 v[60:61], 0
	v_mov_b64_e32 v[62:63], 0
	v_mov_b64_e32 v[64:65], 0
	v_mov_b64_e32 v[66:67], 0
	v_mov_b64_e32 v[68:69], 0
	v_mov_b64_e32 v[70:71], 0
	v_mov_b64_e32 v[72:73], 0
	v_mov_b64_e32 v[74:75], 0
	v_mov_b64_e32 v[76:77], 0
	v_mov_b64_e32 v[78:79], 0
	v_mov_b64_e32 v[80:81], 0
	v_mov_b64_e32 v[82:83], 0
	v_mov_b64_e32 v[84:85], 0
	v_mov_b64_e32 v[86:87], 0
	v_mov_b64_e32 v[88:89], 0
	v_mov_b64_e32 v[90:91], 0
	v_mov_b64_e32 v[92:93], 0
	v_mov_b64_e32 v[94:95], 0
	v_mov_b64_e32 v[96:97], 0
	v_mov_b64_e32 v[98:99], 0
	v_mov_b64_e32 v[100:101], 0
	v_mov_b64_e32 v[102:103], 0
	v_mov_b64_e32 v[112:113], 0
	v_mov_b64_e32 v[114:115], 0
	v_mov_b64_e32 v[116:117], 0
	v_mov_b64_e32 v[118:119], 0
	v_mov_b64_e32 v[120:121], 0
	v_mov_b64_e32 v[122:123], 0
	v_mov_b64_e32 v[132:133], 0
	v_mov_b64_e32 v[134:135], 0
	v_mov_b64_e32 v[136:137], 0
	v_mov_b64_e32 v[138:139], 0
	v_mov_b64_e32 v[140:141], 0
	v_mov_b64_e32 v[142:143], 0
	.p2align 6

;     __device__ __forceinline__ bool next(int i, Unit& u) const { const long L = (long)i * G + c; if (L >= map.total()) return false; map((int)L, u); return true; }
; template <class Epi, class Sched, bool SWAPD = false>
; __device__ __forceinline__ void gemm_phase(LAS unsigned char* lds, const Gemm g, const Sched& S, const Epi& E) {
;     ...
;     for (;;) {
;         const bool has_next = S.next(ui + 1, nxt);
;         const char* nA = has_next ? (const char*)g.A + nxt.aoff : cA; const char* nB = has_next ? (const char*)g.Bt + nxt.boff : cB;
;         const int nt = cur.nt ? cur.nt : ntK;
;         for (int t = 0; t < nt; t += 2) {
;             const bool last = (t == nt - 2);
;             const char* a1 = cA + (size_t)(t + 1) * kstepA;
;             const char* a2 = last ? nA : cA + (size_t)(t + 2) * kstepA; const char* b2 = last ? nB : cB + (size_t)(t + 2) * kstep;
;     ...
; #pragma unroll
;         for (int a = 0; a < 2; ++a)
; #pragma unroll
;             for (int b = 0; b < 2; ++b)
; #pragma unroll
;                 for (int m = 0; m < 4; ++m)
; #pragma unroll
;                     for (int n = 0; n < 2; ++n) acc[a][b][m][n] = (f32x4){0.f, 0.f, 0.f, 0.f};
.LBB0_1862:
	s_add_u32 s28, s18, s24
	s_addc_u32 s29, s19, s25
	s_and_b64 s[30:31], s[6:7], exec
	s_cselect_b32 s21, s29, s37
	s_cselect_b32 s23, s28, s36
	s_add_u32 s30, s13, s26
	s_addc_u32 s31, s33, s27
	s_and_b64 s[40:41], s[6:7], exec
	s_cselect_b32 s54, s31, s39
	s_cselect_b32 s55, s30, s38
	s_add_u32 s36, s36, 0x40080
	s_addc_u32 s37, s37, 0
	s_add_u32 s56, s38, 0x100
	v_mov_b32_e32 v0, 0
	s_addc_u32 s57, s39, 0
	s_mov_b32 s58, -2
	v_mov_b64_e32 v[0:1], 0
	v_mov_b64_e32 v[2:3], 0
	v_mov_b64_e32 v[4:5], 0
	v_mov_b64_e32 v[6:7], 0
	v_mov_b64_e32 v[8:9], 0
	v_mov_b64_e32 v[10:11], 0
	v_mov_b64_e32 v[12:13], 0
	v_mov_b64_e32 v[14:15], 0
	v_mov_b64_e32 v[16:17], 0
	v_mov_b64_e32 v[18:19], 0
	v_mov_b64_e32 v[20:21], 0
	v_mov_b64_e32 v[22:23], 0
	v_mov_b64_e32 v[24:25], 0
	v_mov_b64_e32 v[26:27], 0
	v_mov_b64_e32 v[28:29], 0
	v_mov_b64_e32 v[30:31], 0
	v_mov_b64_e32 v[32:33], 0
	v_mov_b64_e32 v[34:35], 0
	v_mov_b64_e32 v[36:37], 0
	v_mov_b64_e32 v[38:39], 0
	v_mov_b64_e32 v[40:41], 0
	v_mov_b64_e32 v[42:43], 0
	v_mov_b64_e32 v[44:45], 0
	v_mov_b64_e32 v[46:47], 0
	v_mov_b64_e32 v[48:49], 0
	v_mov_b64_e32 v[50:51], 0
	v_mov_b64_e32 v[52:53], 0
	v_mov_b64_e32 v[54:55], 0
	v_mov_b64_e32 v[56:57], 0
	v_mov_b64_e32 v[58:59], 0
	v_mov_b64_e32 v[60:61], 0
	v_mov_b64_e32 v[62:63], 0
	v_mov_b64_e32 v[64:65], 0
	v_mov_b64_e32 v[66:67], 0
	v_mov_b64_e32 v[68:69], 0
	v_mov_b64_e32 v[70:71], 0
	v_mov_b64_e32 v[72:73], 0
	v_mov_b64_e32 v[74:75], 0
	v_mov_b64_e32 v[76:77], 0
	v_mov_b64_e32 v[78:79], 0
	v_mov_b64_e32 v[80:81], 0
	v_mov_b64_e32 v[82:83], 0
	v_mov_b64_e32 v[84:85], 0
	v_mov_b64_e32 v[86:87], 0
	v_mov_b64_e32 v[88:89], 0
	v_mov_b64_e32 v[90:91], 0
	v_mov_b64_e32 v[92:93], 0
	v_mov_b64_e32 v[94:95], 0
	v_mov_b64_e32 v[96:97], 0
	v_mov_b64_e32 v[98:99], 0
	v_mov_b64_e32 v[100:101], 0
	v_mov_b64_e32 v[102:103], 0
	v_mov_b64_e32 v[104:105], 0
	v_mov_b64_e32 v[106:107], 0
	v_mov_b64_e32 v[108:109], 0
	v_mov_b64_e32 v[110:111], 0
	v_mov_b64_e32 v[112:113], 0
	v_mov_b64_e32 v[114:115], 0
	v_mov_b64_e32 v[116:117], 0
	v_mov_b64_e32 v[118:119], 0
	v_mov_b64_e32 v[120:121], 0
	v_mov_b64_e32 v[122:123], 0
	v_mov_b64_e32 v[124:125], 0
	v_mov_b64_e32 v[126:127], 0
	.p2align 6

;     __device__ __forceinline__ bool next(int i, Unit& u) const { const long L = (long)i * G + c; if (L >= map.total()) return false; map((int)L, u); return true; }
; template <class Epi, class Sched, bool SWAPD = false>
; __device__ __forceinline__ void gemm_phase(LAS unsigned char* lds, const Gemm g, const Sched& S, const Epi& E) {
;     ...
;     for (;;) {
;         const bool has_next = S.next(ui + 1, nxt);
;         const char* nA = has_next ? (const char*)g.A + nxt.aoff : cA; const char* nB = has_next ? (const char*)g.Bt + nxt.boff : cB;
;         const int nt = cur.nt ? cur.nt : ntK;
;         for (int t = 0; t < nt; t += 2) {
;             const bool last = (t == nt - 2);
;             const char* a1 = cA + (size_t)(t + 1) * kstepA;
;             const char* a2 = last ? nA : cA + (size_t)(t + 2) * kstepA; const char* b2 = last ? nB : cB + (size_t)(t + 2) * kstep;
;     ...
; #pragma unroll
;         for (int a = 0; a < 2; ++a)
; #pragma unroll
;             for (int b = 0; b < 2; ++b)
; #pragma unroll
;                 for (int m = 0; m < 4; ++m)
; #pragma unroll
;                     for (int n = 0; n < 2; ++n) acc[a][b][m][n] = (f32x4){0.f, 0.f, 0.f, 0.f};
.LBB0_1939:
	s_add_u32 s16, s14, s10
	s_addc_u32 s17, s15, s11
	s_and_b64 s[18:19], s[0:1], exec
	s_cselect_b32 s47, s17, s21
	s_cselect_b32 s48, s16, s20
	s_add_u32 s18, s28, s12
	s_addc_u32 s19, s29, s13
	s_and_b64 s[24:25], s[0:1], exec
	s_cselect_b32 s49, s19, s23
	s_cselect_b32 s50, s18, s22
	s_add_u32 s51, s22, 0x100
	v_mov_b32_e32 v0, 0
	s_addc_u32 s52, s23, 0
	s_mov_b32 s53, -2
	v_mov_b64_e32 v[0:1], 0
	v_mov_b64_e32 v[2:3], 0
	v_mov_b64_e32 v[4:5], 0
	v_mov_b64_e32 v[6:7], 0
	v_mov_b64_e32 v[8:9], 0
	v_mov_b64_e32 v[10:11], 0
	v_mov_b64_e32 v[12:13], 0
	v_mov_b64_e32 v[14:15], 0
	v_mov_b64_e32 v[16:17], 0
	v_mov_b64_e32 v[18:19], 0
	v_mov_b64_e32 v[20:21], 0
	v_mov_b64_e32 v[22:23], 0
	v_mov_b64_e32 v[24:25], 0
	v_mov_b64_e32 v[26:27], 0
	v_mov_b64_e32 v[28:29], 0
	v_mov_b64_e32 v[30:31], 0
	v_mov_b64_e32 v[32:33], 0
	v_mov_b64_e32 v[34:35], 0
	v_mov_b64_e32 v[36:37], 0
	v_mov_b64_e32 v[38:39], 0
	v_mov_b64_e32 v[40:41], 0
	v_mov_b64_e32 v[42:43], 0
	v_mov_b64_e32 v[44:45], 0
	v_mov_b64_e32 v[46:47], 0
	v_mov_b64_e32 v[48:49], 0
	v_mov_b64_e32 v[50:51], 0
	v_mov_b64_e32 v[52:53], 0
	v_mov_b64_e32 v[54:55], 0
	v_mov_b64_e32 v[56:57], 0
	v_mov_b64_e32 v[58:59], 0
	v_mov_b64_e32 v[60:61], 0
	v_mov_b64_e32 v[62:63], 0
	v_mov_b64_e32 v[64:65], 0
	v_mov_b64_e32 v[66:67], 0
	v_mov_b64_e32 v[68:69], 0
	v_mov_b64_e32 v[70:71], 0
	v_mov_b64_e32 v[72:73], 0
	v_mov_b64_e32 v[74:75], 0
	v_mov_b64_e32 v[76:77], 0
	v_mov_b64_e32 v[78:79], 0
	v_mov_b64_e32 v[80:81], 0
	v_mov_b64_e32 v[82:83], 0
	v_mov_b64_e32 v[84:85], 0
	v_mov_b64_e32 v[86:87], 0
	v_mov_b64_e32 v[88:89], 0
	v_mov_b64_e32 v[90:91], 0
	v_mov_b64_e32 v[92:93], 0
	v_mov_b64_e32 v[94:95], 0
	v_mov_b64_e32 v[96:97], 0
	v_mov_b64_e32 v[98:99], 0
	v_mov_b64_e32 v[100:101], 0
	v_mov_b64_e32 v[102:103], 0
	v_mov_b64_e32 v[104:105], 0
	v_mov_b64_e32 v[106:107], 0
	v_mov_b64_e32 v[108:109], 0
	v_mov_b64_e32 v[110:111], 0
	v_mov_b64_e32 v[112:113], 0
	v_mov_b64_e32 v[114:115], 0
	v_mov_b64_e32 v[116:117], 0
	v_mov_b64_e32 v[118:119], 0
	v_mov_b64_e32 v[120:121], 0
	v_mov_b64_e32 v[122:123], 0
	v_mov_b64_e32 v[124:125], 0
	v_mov_b64_e32 v[126:127], 0
	.p2align 6
